# PH2 V transposes spread over all workgroups (two waves per workgroup) instead of all eight waves of the first 64 workgroups
# speedup vs baseline: 1.0087x; 1.0087x over previous
; __global__ void __launch_bounds__(512, 2) fwd_megakernel(Args args) {
;     ...
;             for (int it = gw; it < 512; it += NGW) {
;                 const int bk = it >> 6, tt = it & 63, b = bk >> 1, kvh = bk & 1;
;                 transpose64x128(P + ((size_t)b * S_ + 64 * tt) * NPROJ + PC_V + kvh * 128, NPROJ, VT + (size_t)bk * 128 * S_ + 64 * tt, S_, lane);
.LBB0_549:
	s_mul_i32 s3, s9, s66
	s_add_i32 s3, s3, s86
	s_cmpk_gt_i32 s3, 0x1ff
	s_mov_b32 s16, 0x10000
	s_movk_i32 s17, 0x6000
	s_mov_b32 s18, 0x18000
	s_mov_b32 s19, 0x8000
	s_mov_b32 s22, 0xa000
	s_mov_b32 s23, 0xc000
	s_mov_b32 s29, 0xe000
	s_cbranch_scc1 .LBB0_552
	s_add_u32 s0, s44, 0x21100000
	s_addc_u32 s1, s45, 0
	v_mul_u32_u24_e32 v0, 0x1100, v64
	s_mul_i32 s3, s9, s66
	s_add_i32 s3, s3, s86
	s_lshl_b32 s2, s3, 6
	v_lshlrev_b32_e32 v160, 1, v0
	v_lshlrev_b32_e32 v60, 1, v64
